# compress-MLP K loop: all 18 operand loads of an iteration issued up front with counted waits (was load/wait/mfma ladder); + EpiResid, attention PV, bias1 edits
# speedup vs baseline: 1.0162x; 1.0058x over previous
; DI void prep_phase(const int wv, const Params& p, int l, LAS unsigned char* lds) {
;     ...
; #pragma unroll 2
;             for (int kk = 0; kk < 16; ++kk) { const int ks = 16 * wave + kk;
;                 const bf16x8 a = *(const bf16x8*)(Arow + (size_t)(ks >> 2) * PWID + (ks & 3) * 32);
; #pragma unroll
;                 for (int nt = 0; nt < 8; ++nt) { const bf16x8 bb = *(const bf16x8*)(Brow + (size_t)nt * 16 * 4096 + ks * 32);
;                     acc[nt] = __builtin_amdgcn_mfma_f32_16x16x32_bf16(a, bb, acc[nt], 0, 0, 0); }
;             }
.LBB0_362:
	s_sub_i32 s17, s1, 32
	v_ashrrev_i32_e32 v50, 2, v80
	s_and_b32 s17, s17, 64
	v_mad_i64_i32 v[50:51], s[18:19], v50, s68, v[46:47]
	s_lshl_b32 s86, s17, 1
	v_lshl_add_u64 v[50:51], v[50:51], 0, s[86:87]
	global_load_dwordx4 v[82:85], v[50:51], off
	v_add_u32_e32 v81, 1, v80
	v_ashrrev_i32_e32 v81, 2, v81
	s_and_b32 s17, s1, 0x60
	s_lshl_b32 s86, s17, 1
	v_mad_i64_i32 v[52:53], s[18:19], v81, s68, v[46:47]
	v_lshl_add_u64 v[52:53], v[52:53], 0, s[86:87]
	global_load_dwordx4 v[86:89], v[52:53], off
	v_add_u32_e32 v80, 2, v80
	v_lshl_add_u64 v[90:91], v[48:49], 0, s[12:13]
	s_mov_b32 s17, 0x5b00000
	v_add_co_u32_e32 v54, vcc, s17, v90
	s_mov_b32 s17, 0x5b20000
	s_nop 0
	v_addc_co_u32_e32 v55, vcc, 0, v91, vcc
	v_add_co_u32_e32 v56, vcc, s17, v90
	s_mov_b32 s17, 0x5b40000
	s_nop 0
	v_addc_co_u32_e32 v57, vcc, 0, v91, vcc
	v_add_co_u32_e32 v58, vcc, s17, v90
	s_mov_b32 s17, 0x5b60000
	s_nop 0
	v_addc_co_u32_e32 v59, vcc, 0, v91, vcc
	v_add_co_u32_e32 v60, vcc, s17, v90
	s_mov_b32 s17, 0x5b80000
	s_nop 0
	v_addc_co_u32_e32 v61, vcc, 0, v91, vcc
	v_add_co_u32_e32 v62, vcc, s17, v90
	s_mov_b32 s17, 0x5ba0000
	s_nop 0
	v_addc_co_u32_e32 v63, vcc, 0, v91, vcc
	v_add_co_u32_e32 v64, vcc, s17, v90
	s_mov_b32 s17, 0x5bc0000
	s_nop 0
	v_addc_co_u32_e32 v65, vcc, 0, v91, vcc
	v_add_co_u32_e32 v156, vcc, s17, v90
	s_mov_b32 s17, 0x5be0000
	s_nop 0
	v_addc_co_u32_e32 v157, vcc, 0, v91, vcc
	v_add_co_u32_e32 v158, vcc, s17, v90
	s_mov_b32 s17, 0x5c00000
	s_nop 0
	v_addc_co_u32_e32 v159, vcc, 0, v91, vcc
	global_load_dwordx4 v[92:95], v[54:55], off
	global_load_dwordx4 v[96:99], v[56:57], off
	global_load_dwordx4 v[100:103], v[58:59], off
	global_load_dwordx4 v[104:107], v[60:61], off
	global_load_dwordx4 v[108:111], v[62:63], off
	global_load_dwordx4 v[112:115], v[64:65], off
	global_load_dwordx4 v[116:119], v[156:157], off
	global_load_dwordx4 v[120:123], v[158:159], off
	global_load_dwordx4 v[124:127], v[54:55], off offset:64
	global_load_dwordx4 v[128:131], v[56:57], off offset:64
	global_load_dwordx4 v[132:135], v[58:59], off offset:64
	global_load_dwordx4 v[136:139], v[60:61], off offset:64
	global_load_dwordx4 v[140:143], v[62:63], off offset:64
	global_load_dwordx4 v[144:147], v[64:65], off offset:64
	global_load_dwordx4 v[148:151], v[156:157], off offset:64
	global_load_dwordx4 v[152:155], v[158:159], off offset:64
	s_add_u32 s12, s12, 0x80
	s_addc_u32 s13, s13, 0
	s_add_i32 s1, s1, 64
	s_waitcnt vmcnt(15)
	v_mfma_f32_16x16x32_bf16 v[16:19], v[82:85], v[92:95], v[16:19]
	s_waitcnt vmcnt(14)
	v_mfma_f32_16x16x32_bf16 v[20:23], v[82:85], v[96:99], v[20:23]
	s_waitcnt vmcnt(13)
	v_mfma_f32_16x16x32_bf16 v[12:15], v[82:85], v[100:103], v[12:15]
	s_waitcnt vmcnt(12)
	v_mfma_f32_16x16x32_bf16 v[8:11], v[82:85], v[104:107], v[8:11]
	s_waitcnt vmcnt(11)
	v_mfma_f32_16x16x32_bf16 v[24:27], v[82:85], v[108:111], v[24:27]
	s_waitcnt vmcnt(10)
	v_mfma_f32_16x16x32_bf16 v[28:31], v[82:85], v[112:115], v[28:31]
	s_waitcnt vmcnt(9)
	v_mfma_f32_16x16x32_bf16 v[0:3], v[82:85], v[116:119], v[0:3]
	s_waitcnt vmcnt(8)
	v_mfma_f32_16x16x32_bf16 v[4:7], v[82:85], v[120:123], v[4:7]
	s_waitcnt vmcnt(7)
	v_mfma_f32_16x16x32_bf16 v[16:19], v[86:89], v[124:127], v[16:19]
	s_waitcnt vmcnt(6)
	v_mfma_f32_16x16x32_bf16 v[20:23], v[86:89], v[128:131], v[20:23]
	s_waitcnt vmcnt(5)
	v_mfma_f32_16x16x32_bf16 v[12:15], v[86:89], v[132:135], v[12:15]
	s_waitcnt vmcnt(4)
	v_mfma_f32_16x16x32_bf16 v[8:11], v[86:89], v[136:139], v[8:11]
	s_waitcnt vmcnt(3)
	v_mfma_f32_16x16x32_bf16 v[24:27], v[86:89], v[140:143], v[24:27]
	s_waitcnt vmcnt(2)
	v_mfma_f32_16x16x32_bf16 v[28:31], v[86:89], v[144:147], v[28:31]
	s_waitcnt vmcnt(1)
	v_mfma_f32_16x16x32_bf16 v[0:3], v[86:89], v[148:151], v[0:3]
	s_waitcnt vmcnt(0)
	v_mfma_f32_16x16x32_bf16 v[4:7], v[86:89], v[152:155], v[4:7]
	s_cmpk_eq_i32 s12, 0x400
	s_cbranch_scc0 .LBB0_362
	v_add_u32_e32 v46, 0x4000, v78
	s_and_b32 s12, s14, 0xffffff80
	s_waitcnt lgkmcnt(0)
	s_barrier
; DI void prep_phase(const int wv, const Params& p, int l, LAS unsigned char* lds) {
;     ...
;             __syncthreads();
; #pragma unroll
;             for (int nt = 0; nt < 8; ++nt)
; #pragma unroll
;                 for (int i = 0; i < 4; ++i) part[(wave * 16 + 4 * kq + i) * 128 + 16 * nt + r16] = acc[nt][i];
;             __syncthreads();
;             { const int row = tid >> 5, n4 = (tid & 31) * 4; f32x4 s = *(const f32x4*)(bias1 + kv * 128 + n4);
; #pragma unroll
;               for (int w = 0; w < 8; ++w) s += *(const LAS f32x4*)(part + (w * 16 + row) * 128 + n4);
;               u32x2 hv; hv.x = pk2(silu_f(s.x), silu_f(s.y)); hv.y = pk2(silu_f(s.z), silu_f(s.w));
;               *(LAS u32x2*)(Hs + row * 136 + n4) = hv; }
;             __syncthreads();
;             f32x4 acc2 = {0.f, 0.f, 0.f, 0.f};
; #pragma unroll
;             for (int ks = 0; ks < 4; ++ks) {
;                 const bf16x8 a = *(const LAS bf16x8*)(Hs + r16 * 136 + ks * 32 + 8 * kq);
;                 const bf16x8 bb = *(const bf16x8*)(W2t + (size_t)(16 * wave + r16) * 128 + ks * 32 + 8 * kq);
;                 acc2 = __builtin_amdgcn_mfma_f32_16x16x32_bf16(a, bb, acc2, 0, 0, 0);
;             }
;             const int n = 16 * wave + r16;
;             if (kv == 0) {
;                 float ss[4];
; #pragma unroll
;                 for (int i = 0; i < 4; ++i) { float s = acc2[i] * acc2[i]; s += __shfl_xor(s, 1); s += __shfl_xor(s, 2); s += __shfl_xor(s, 4); s += __shfl_xor(s, 8); ss[i] = s; }
;                 if (r16 == 0) {
; #pragma unroll
;                     for (int i = 0; i < 4; ++i) red[wave * 16 + 4 * kq + i] = ss[i]; }
;                 __syncthreads();
;                 const float gn = p.k_gain[(l * 3 + 0) * 128 + n];
; #pragma unroll
;                 for (int i = 0; i < 4; ++i) { const int row = 4 * kq + i; float s = 0.f;
; #pragma unroll
;                     for (int w = 0; w < 8; ++w) s += red[w * 16 + row];
;                     const float rstd = rsqrtf(s * (1.f / 128.f) + 1e-6f); const int c = c0 + row;
;                     const float v = (c < 255) ? acc2[i] * rstd * gn : 0.f;
;                     kcmp[(((size_t)b * 2 + g) * 256 + c) * 128 + n] = (bf16_t)(pk2(v, 0.f) & 0xffffu); }
;             } else {
;                 float v[4];
; #pragma unroll
;                 for (int i = 0; i < 4; ++i) v[i] = (c0 + 4 * kq + i < 255) ? acc2[i] : 0.f;
	ds_write2_b32 v46, v16, v20 offset1:16
	ds_write2_b32 v46, v17, v21 offset0:128 offset1:144
	v_add_u32_e32 v16, 0x4400, v78
	s_ashr_i32 s13, s12, 31
	ds_write2_b32 v16, v18, v22 offset1:16
	ds_write2_b32 v16, v19, v23 offset0:128 offset1:144
	ds_write2_b32 v46, v12, v8 offset0:32 offset1:48
	ds_write2_b32 v46, v13, v9 offset0:160 offset1:176
	ds_write2_b32 v16, v14, v10 offset0:32 offset1:48
	ds_write2_b32 v16, v15, v11 offset0:160 offset1:176
	ds_write2_b32 v46, v24, v28 offset0:64 offset1:80
	ds_write2_b32 v46, v25, v29 offset0:192 offset1:208
	ds_write2_b32 v16, v26, v30 offset0:64 offset1:80
	ds_write2_b32 v16, v27, v31 offset0:192 offset1:208
	ds_write2_b32 v46, v0, v4 offset0:96 offset1:112
	ds_write2_b32 v46, v1, v5 offset0:224 offset1:240
	ds_write2_b32 v16, v2, v6 offset0:96 offset1:112
	ds_write2_b32 v16, v3, v7 offset0:224 offset1:240
	v_lshl_add_u64 v[0:1], s[12:13], 2, v[34:35]
	s_waitcnt lgkmcnt(0)
	s_barrier
	global_load_dwordx4 v[0:3], v[0:1], off
	ds_read_b128 v[4:7], v70 offset:16384
	s_lshl_b64 s[10:11], s[10:11], 15
	v_lshl_add_u64 v[12:13], v[38:39], 0, s[10:11]
	s_mov_b64 s[10:11], -1
	s_and_b64 vcc, exec, s[8:9]
	s_waitcnt vmcnt(0) lgkmcnt(0)
	v_pk_add_f32 v[6:7], v[2:3], v[6:7]
	v_pk_add_f32 v[4:5], v[0:1], v[4:5]
	ds_read_b128 v[0:3], v70 offset:24576
	s_waitcnt lgkmcnt(0)
	v_pk_add_f32 v[6:7], v[6:7], v[2:3]
	v_pk_add_f32 v[4:5], v[4:5], v[0:1]
	ds_read_b128 v[0:3], v70 offset:32768
	s_waitcnt lgkmcnt(0)
	v_pk_add_f32 v[6:7], v[6:7], v[2:3]
	v_pk_add_f32 v[4:5], v[4:5], v[0:1]
	ds_read_b128 v[0:3], v70 offset:40960
	s_waitcnt lgkmcnt(0)
	v_pk_add_f32 v[6:7], v[6:7], v[2:3]
	v_pk_add_f32 v[4:5], v[4:5], v[0:1]
	ds_read_b128 v[0:3], v70 offset:49152
	s_waitcnt lgkmcnt(0)
	v_pk_add_f32 v[6:7], v[6:7], v[2:3]
	v_pk_add_f32 v[4:5], v[4:5], v[0:1]
	ds_read_b128 v[0:3], v70 offset:57344
	s_waitcnt lgkmcnt(0)
	v_pk_add_f32 v[6:7], v[6:7], v[2:3]
	v_pk_add_f32 v[4:5], v[4:5], v[0:1]
	ds_read_b128 v[0:3], v71 offset:49152
	s_waitcnt lgkmcnt(0)
	v_pk_add_f32 v[6:7], v[6:7], v[2:3]
	v_pk_add_f32 v[4:5], v[4:5], v[0:1]
	ds_read_b128 v[0:3], v71 offset:57344
	s_waitcnt lgkmcnt(0)
	v_pk_add_f32 v[0:1], v[4:5], v[0:1]
	s_nop 0
	v_mul_f32_e32 v4, 0xbfb8aa3b, v0
	v_mul_f32_e32 v5, 0xbfb8aa3b, v1
	v_exp_f32_e32 v4, v4
	v_exp_f32_e32 v5, v5
	v_pk_add_f32 v[2:3], v[6:7], v[2:3]
	v_add_f32_e32 v4, 1.0, v4
	v_add_f32_e32 v5, 1.0, v5
	v_rcp_f32_e32 v4, v4
	v_rcp_f32_e32 v5, v5
	s_nop 0
	v_pk_mul_f32 v[0:1], v[0:1], v[4:5]
	s_nop 0
	v_cvt_pk_bf16_f32 v0, v0, v1
	v_mul_f32_e32 v1, 0xbfb8aa3b, v2
	v_exp_f32_e32 v1, v1
	s_nop 0
	v_add_f32_e32 v1, 1.0, v1
	v_rcp_f32_e32 v4, v1
	v_mul_f32_e32 v1, 0xbfb8aa3b, v3
	v_exp_f32_e32 v1, v1
	s_nop 0
	v_add_f32_e32 v1, 1.0, v1
	v_rcp_f32_e32 v5, v1
	s_nop 0
	v_pk_mul_f32 v[2:3], v[2:3], v[4:5]
	s_nop 0
	v_cvt_pk_bf16_f32 v1, v2, v3
	ds_write_b64 v72, v[0:1]
	s_waitcnt lgkmcnt(0)
	s_barrier
	global_load_dwordx4 v[4:7], v[12:13], off
	global_load_dwordx4 v[8:11], v[12:13], off offset:64
	ds_read_b128 v[0:3], v73
	s_waitcnt vmcnt(1) lgkmcnt(0)
	v_mfma_f32_16x16x32_bf16 v[0:3], v[0:3], v[4:7], 0
	ds_read_b128 v[4:7], v73 offset:64
	s_waitcnt vmcnt(0) lgkmcnt(0)
	v_mfma_f32_16x16x32_bf16 v[0:3], v[4:7], v[8:11], v[0:3]
	global_load_dwordx4 v[8:11], v[12:13], off offset:128
	ds_read_b128 v[4:7], v73 offset:128
	s_waitcnt vmcnt(0) lgkmcnt(0)
	v_mfma_f32_16x16x32_bf16 v[0:3], v[4:7], v[8:11], v[0:3]
	global_load_dwordx4 v[8:11], v[12:13], off offset:192
	ds_read_b128 v[4:7], v73 offset:192
	v_or_b32_e32 v12, s15, v32
	s_waitcnt vmcnt(0) lgkmcnt(0)
	v_mfma_f32_16x16x32_bf16 v[0:3], v[4:7], v[8:11], v[0:3]
	s_cbranch_vccz .LBB0_365
	s_movk_i32 s1, 0xfc
	v_cmp_ne_u32_e32 vcc, s1, v12
	v_lshl_add_u64 v[6:7], s[6:7], 0, v[36:37]
	s_lshl_b32 s1, s16, 17
	v_readlane_b32 s6, v253, 63
	s_add_u32 s6, s6, s1
	v_readlane_b32 s1, v254, 0
	v_lshlrev_b64 v[6:7], 9, v[6:7]
	s_addc_u32 s7, s1, 0
	v_lshl_add_u64 v[6:7], s[6:7], 0, v[6:7]
	s_lshl_b32 s86, s15, 1
	v_cndmask_b32_e32 v5, 0, v3, vcc
	v_lshl_add_u64 v[6:7], v[6:7], 0, s[86:87]
	v_lshlrev_b32_e32 v8, 1, v32
	v_mov_b32_e32 v9, v161
	v_cvt_pk_bf16_f32 v4, v0, v1
	v_cvt_pk_bf16_f32 v5, v2, v5
	v_lshl_add_u64 v[6:7], v[6:7], 0, v[8:9]
	global_store_dwordx2 v[6:7], v[4:5], off
	s_cbranch_execnz .LBB0_360
	s_branch .LBB0_366
